# mixer phase: workgroups 256..511 sleep ~10us before first queue grab so scan items land one per CU (timing-only change)
# speedup vs baseline: 1.0357x; 1.0140x over previous
.LBB0_299:
	s_or_b64 exec, exec, s[4:5]
	v_readlane_b32 s4, v254, 57
	v_readlane_b32 s5, v254, 58
	s_lshl_b32 s90, s4, 4
	s_lshl_b64 s[4:5], s[90:91], 2
	s_add_u32 s4, s42, s4
	s_addc_u32 s5, s43, s5
	v_readlane_b32 s6, v254, 29
	s_add_u32 s6, s4, s6
	s_addc_u32 s7, s5, 0
	v_writelane_b32 v254, s6, 61
	s_barrier
	s_nop 0
	v_writelane_b32 v254, s7, 62
	s_nop 0
	v_readlane_b32 s6, v254, 31
	s_add_u32 s6, s4, s6
	s_addc_u32 s7, s5, 0
	v_writelane_b32 v254, s6, 63
	s_nop 1
	v_writelane_b32 v255, s7, 0
	v_readlane_b32 s6, v254, 33
	s_add_u32 s6, s4, s6
	s_addc_u32 s7, s5, 0
	v_writelane_b32 v255, s6, 1
	s_nop 1
	v_writelane_b32 v255, s7, 2
	v_readlane_b32 s6, v254, 35
	s_add_u32 s6, s4, s6
	s_addc_u32 s7, s5, 0
	v_writelane_b32 v255, s6, 3
	s_nop 1
	v_writelane_b32 v255, s7, 4
	v_readlane_b32 s6, v254, 37
	s_add_u32 s6, s4, s6
	s_addc_u32 s7, s5, 0
	v_writelane_b32 v255, s6, 5
	s_nop 1
	v_writelane_b32 v255, s7, 6
	v_readlane_b32 s6, v254, 39
	s_add_u32 s6, s4, s6
	s_addc_u32 s7, s5, 0
	v_writelane_b32 v255, s6, 7
	s_nop 1
	v_writelane_b32 v255, s7, 8
	v_readlane_b32 s6, v254, 41
	s_add_u32 s6, s4, s6
	s_addc_u32 s7, s5, 0
	v_writelane_b32 v255, s6, 9
	s_nop 1
	v_writelane_b32 v255, s7, 10
	v_readlane_b32 s6, v254, 43
	s_add_u32 s4, s4, s6
	s_addc_u32 s5, s5, 0
	v_writelane_b32 v255, s4, 11
	s_nop 1
	v_writelane_b32 v255, s5, 12
	v_readlane_b32 s6, v254, 13
	s_cmpk_lt_u32 s6, 0x100
	s_cbranch_scc1 .Lmx_nodelay
	s_sleep 127
	s_sleep 127
	s_sleep 127
.Lmx_nodelay:
	s_branch .LBB0_302
.LBB0_300:
	s_or_b64 exec, exec, s[4:5]
	s_barrier
	s_setprio 0
	v_readlane_b32 s42, v253, 8
	v_readlane_b32 s43, v253, 9
